# HGRN2 chunk scan: decay-pass q re-reads issued together ahead of the stores
# baseline (speedup 1.0000x reference)
.LBB0_466:
	s_or_b64 exec, exec, s[4:5]
	s_waitcnt lgkmcnt(0)
	ds_read_u16 v224, v43
	ds_read_u16 v225, v45
	ds_read_u16 v226, v76
	ds_read_u16 v227, v77
	ds_read_u16 v228, v78
	ds_read_u16 v229, v79
	ds_read_u16 v230, v80
	ds_read_u16 v231, v81
	ds_read_u16 v232, v82
	ds_read_u16 v233, v43 offset:2448
	ds_read_u16 v234, v43 offset:2720
	ds_read_u16 v235, v43 offset:2992
	ds_read_u16 v236, v43 offset:3264
	ds_read_u16 v237, v43 offset:3536
	ds_read_u16 v238, v43 offset:3808
	ds_read_u16 v239, v43 offset:4080
	v_mul_f32_e32 v67, v64, v102
	v_rcp_f32_e32 v66, v67
	v_pk_add_f32 v[64:65], v[64:65], 1.0 op_sel_hi:[1,0] neg_lo:[1,0] neg_hi:[1,0]
	v_pk_add_f32 v[62:63], v[62:63], 1.0 op_sel_hi:[1,0] neg_lo:[1,0] neg_hi:[1,0]
	s_waitcnt lgkmcnt(14)
	v_lshlrev_b32_e32 v68, 16, v224
	v_mul_f32_e32 v67, v67, v68
	v_bfe_u32 v68, v67, 16, 1
	v_add3_u32 v67, v67, v68, s0
	v_mul_f32_e32 v68, v116, v102
	ds_write_b16_d16_hi v43, v67
	v_rcp_f32_e32 v67, v68
	v_pk_add_f32 v[60:61], v[60:61], 1.0 op_sel_hi:[1,0] neg_lo:[1,0] neg_hi:[1,0]
	v_pk_add_f32 v[58:59], v[58:59], 1.0 op_sel_hi:[1,0] neg_lo:[1,0] neg_hi:[1,0]
	v_pk_add_f32 v[56:57], v[56:57], 1.0 op_sel_hi:[1,0] neg_lo:[1,0] neg_hi:[1,0]
	v_pk_mul_f32 v[64:65], v[64:65], v[66:67]
	v_pk_add_f32 v[54:55], v[54:55], 1.0 op_sel_hi:[1,0] neg_lo:[1,0] neg_hi:[1,0]
	v_and_b32_sdwa v67, v64, v190 dst_sel:DWORD dst_unused:UNUSED_PAD src0_sel:WORD_1 src1_sel:DWORD
	v_add3_u32 v67, v64, v67, s0
	v_lshrrev_b32_e32 v64, 16, v67
	ds_write_b16 v43, v64 offset:17408
	v_and_b32_sdwa v66, v65, v190 dst_sel:DWORD dst_unused:UNUSED_PAD src0_sel:WORD_1 src1_sel:DWORD
	v_add3_u32 v66, v65, v66, s0
	v_lshrrev_b32_e32 v65, 16, v66
	v_pk_add_f32 v[52:53], v[52:53], 1.0 op_sel_hi:[1,0] neg_lo:[1,0] neg_hi:[1,0]
	v_lshlrev_b32_e32 v64, 16, v225
	v_mul_f32_e32 v64, v68, v64
	v_bfe_u32 v68, v64, 16, 1
	v_add3_u32 v64, v64, v68, s0
	ds_write_b16_d16_hi v45, v64
	ds_write_b16 v45, v65 offset:17408
	v_mul_f32_e32 v65, v115, v102
	v_rcp_f32_e32 v64, v65
	v_pk_add_f32 v[50:51], v[50:51], 1.0 op_sel_hi:[1,0] neg_lo:[1,0] neg_hi:[1,0]
	s_waitcnt lgkmcnt(14)
	v_lshlrev_b32_e32 v68, 16, v226
	v_mul_f32_e32 v65, v65, v68
	v_bfe_u32 v68, v65, 16, 1
	v_add3_u32 v65, v65, v68, s0
	v_mul_f32_e32 v68, v114, v102
	ds_write_b16_d16_hi v76, v65
	v_rcp_f32_e32 v65, v68
	s_nop 0
	v_pk_mul_f32 v[62:63], v[62:63], v[64:65]
	s_nop 0
	v_and_b32_sdwa v65, v62, v190 dst_sel:DWORD dst_unused:UNUSED_PAD src0_sel:WORD_1 src1_sel:DWORD
	v_add3_u32 v65, v62, v65, s0
	v_lshrrev_b32_e32 v62, 16, v65
	ds_write_b16 v76, v62 offset:17408
	v_and_b32_sdwa v64, v63, v190 dst_sel:DWORD dst_unused:UNUSED_PAD src0_sel:WORD_1 src1_sel:DWORD
	v_add3_u32 v64, v63, v64, s0
	v_lshrrev_b32_e32 v63, 16, v64
	v_lshlrev_b32_e32 v62, 16, v227
	v_mul_f32_e32 v62, v68, v62
	v_bfe_u32 v68, v62, 16, 1
	v_add3_u32 v62, v62, v68, s0
	ds_write_b16_d16_hi v77, v62
	ds_write_b16 v77, v63 offset:17408
	v_mul_f32_e32 v63, v113, v102
	v_rcp_f32_e32 v62, v63
	v_lshlrev_b32_e32 v68, 16, v228
	v_mul_f32_e32 v63, v63, v68
	v_bfe_u32 v68, v63, 16, 1
	v_add3_u32 v63, v63, v68, s0
	v_mul_f32_e32 v68, v112, v102
	ds_write_b16_d16_hi v78, v63
	v_rcp_f32_e32 v63, v68
	s_nop 0
	v_pk_mul_f32 v[60:61], v[60:61], v[62:63]
	s_nop 0
	v_and_b32_sdwa v63, v60, v190 dst_sel:DWORD dst_unused:UNUSED_PAD src0_sel:WORD_1 src1_sel:DWORD
	v_add3_u32 v63, v60, v63, s0
	v_lshrrev_b32_e32 v60, 16, v63
	ds_write_b16 v78, v60 offset:17408
	v_and_b32_sdwa v62, v61, v190 dst_sel:DWORD dst_unused:UNUSED_PAD src0_sel:WORD_1 src1_sel:DWORD
	v_add3_u32 v62, v61, v62, s0
	v_lshrrev_b32_e32 v61, 16, v62
	v_lshlrev_b32_e32 v60, 16, v229
	v_mul_f32_e32 v60, v68, v60
	v_bfe_u32 v68, v60, 16, 1
	v_add3_u32 v60, v60, v68, s0
	ds_write_b16_d16_hi v79, v60
	ds_write_b16 v79, v61 offset:17408
	v_mul_f32_e32 v61, v111, v102
	v_rcp_f32_e32 v60, v61
	s_waitcnt lgkmcnt(14)
	v_lshlrev_b32_e32 v68, 16, v230
	v_mul_f32_e32 v61, v61, v68
	v_bfe_u32 v68, v61, 16, 1
	v_add3_u32 v61, v61, v68, s0
	v_mul_f32_e32 v68, v110, v102
	ds_write_b16_d16_hi v80, v61
	v_rcp_f32_e32 v61, v68
	s_nop 0
	v_pk_mul_f32 v[58:59], v[58:59], v[60:61]
	s_nop 0
	v_and_b32_sdwa v61, v58, v190 dst_sel:DWORD dst_unused:UNUSED_PAD src0_sel:WORD_1 src1_sel:DWORD
	v_and_b32_sdwa v60, v59, v190 dst_sel:DWORD dst_unused:UNUSED_PAD src0_sel:WORD_1 src1_sel:DWORD
	v_add3_u32 v58, v58, v61, s0
	v_add3_u32 v59, v59, v60, s0
	v_lshrrev_b32_e32 v60, 16, v58
	ds_write_b16 v80, v60 offset:17408
	v_lshrrev_b32_e32 v61, 16, v59
	v_lshlrev_b32_e32 v60, 16, v231
	v_mul_f32_e32 v60, v68, v60
	v_bfe_u32 v68, v60, 16, 1
	v_add3_u32 v60, v60, v68, s0
	ds_write_b16_d16_hi v81, v60
	ds_write_b16 v81, v61 offset:17408
	v_perm_b32 v61, v59, v58, s19
	v_perm_b32 v60, v62, v63, s19
	v_perm_b32 v59, v64, v65, s19
	v_perm_b32 v58, v66, v67, s19
	ds_write_b128 v94, v[58:61] offset:34816
	v_mul_f32_e32 v59, v109, v102
	v_rcp_f32_e32 v58, v59
	v_lshlrev_b32_e32 v60, 16, v232
	v_mul_f32_e32 v59, v59, v60
	v_bfe_u32 v60, v59, 16, 1
	v_add3_u32 v59, v59, v60, s0
	v_mul_f32_e32 v60, v108, v102
	ds_write_b16_d16_hi v82, v59
	v_rcp_f32_e32 v59, v60
	s_nop 0
	v_pk_mul_f32 v[56:57], v[56:57], v[58:59]
	s_nop 0
	v_and_b32_sdwa v59, v56, v190 dst_sel:DWORD dst_unused:UNUSED_PAD src0_sel:WORD_1 src1_sel:DWORD
	v_add3_u32 v59, v56, v59, s0
	v_lshrrev_b32_e32 v56, 16, v59
	ds_write_b16 v82, v56 offset:17408
	v_and_b32_sdwa v58, v57, v190 dst_sel:DWORD dst_unused:UNUSED_PAD src0_sel:WORD_1 src1_sel:DWORD
	v_add3_u32 v58, v57, v58, s0
	v_lshrrev_b32_e32 v57, 16, v58
	v_lshlrev_b32_e32 v56, 16, v233
	v_mul_f32_e32 v56, v60, v56
	v_bfe_u32 v60, v56, 16, 1
	v_add3_u32 v56, v56, v60, s0
	ds_write_b16_d16_hi v43, v56 offset:2448
	ds_write_b16 v43, v57 offset:19856
	v_mul_f32_e32 v57, v107, v102
	v_rcp_f32_e32 v56, v57
	v_lshlrev_b32_e32 v60, 16, v234
	v_mul_f32_e32 v57, v57, v60
	v_bfe_u32 v60, v57, 16, 1
	v_add3_u32 v57, v57, v60, s0
	v_mul_f32_e32 v60, v106, v102
	ds_write_b16_d16_hi v43, v57 offset:2720
	v_rcp_f32_e32 v57, v60
	v_lshlrev_b32_e32 v61, 16, v235
	v_mul_f32_e32 v60, v60, v61
	v_bfe_u32 v61, v60, 16, 1
	v_pk_mul_f32 v[54:55], v[54:55], v[56:57]
	v_add3_u32 v60, v60, v61, s0
	v_and_b32_sdwa v57, v54, v190 dst_sel:DWORD dst_unused:UNUSED_PAD src0_sel:WORD_1 src1_sel:DWORD
	v_and_b32_sdwa v56, v55, v190 dst_sel:DWORD dst_unused:UNUSED_PAD src0_sel:WORD_1 src1_sel:DWORD
	v_add3_u32 v57, v54, v57, s0
	v_add3_u32 v56, v55, v56, s0
	v_lshrrev_b32_e32 v54, 16, v57
	ds_write_b16_d16_hi v43, v60 offset:2992
	v_lshrrev_b32_e32 v55, 16, v56
	ds_write_b16 v43, v54 offset:20128
	ds_write_b16 v43, v55 offset:20400
	v_mul_f32_e32 v55, v105, v102
	v_rcp_f32_e32 v54, v55
	v_lshlrev_b32_e32 v60, 16, v236
	v_mul_f32_e32 v55, v55, v60
	v_bfe_u32 v60, v55, 16, 1
	v_add3_u32 v55, v55, v60, s0
	v_mul_f32_e32 v60, v104, v102
	ds_write_b16_d16_hi v43, v55 offset:3264
	v_rcp_f32_e32 v55, v60
	v_lshlrev_b32_e32 v61, 16, v237
	v_mul_f32_e32 v60, v60, v61
	v_bfe_u32 v61, v60, 16, 1
	v_pk_mul_f32 v[52:53], v[52:53], v[54:55]
	v_add3_u32 v60, v60, v61, s0
	v_and_b32_sdwa v55, v52, v190 dst_sel:DWORD dst_unused:UNUSED_PAD src0_sel:WORD_1 src1_sel:DWORD
	v_and_b32_sdwa v54, v53, v190 dst_sel:DWORD dst_unused:UNUSED_PAD src0_sel:WORD_1 src1_sel:DWORD
	v_add3_u32 v55, v52, v55, s0
	v_add3_u32 v54, v53, v54, s0
	v_lshrrev_b32_e32 v52, 16, v55
	ds_write_b16_d16_hi v43, v60 offset:3536
	v_lshrrev_b32_e32 v53, 16, v54
	ds_write_b16 v43, v52 offset:20672
	ds_write_b16 v43, v53 offset:20944
	v_mul_f32_e32 v53, v103, v102
	v_rcp_f32_e32 v52, v53
	s_waitcnt lgkmcnt(14)
	v_lshlrev_b32_e32 v60, 16, v238
	v_mul_f32_e32 v53, v53, v60
	v_bfe_u32 v60, v53, 16, 1
	v_add3_u32 v53, v53, v60, s0
	v_mul_f32_e32 v60, v101, v102
	ds_write_b16_d16_hi v43, v53 offset:3808
	v_rcp_f32_e32 v53, v60
	v_lshlrev_b32_e32 v61, 16, v239
	v_mul_f32_e32 v60, v60, v61
	v_bfe_u32 v61, v60, 16, 1
	v_pk_mul_f32 v[50:51], v[50:51], v[52:53]
	v_add3_u32 v60, v60, v61, s0
	v_and_b32_sdwa v52, v51, v190 dst_sel:DWORD dst_unused:UNUSED_PAD src0_sel:WORD_1 src1_sel:DWORD
	v_and_b32_sdwa v53, v50, v190 dst_sel:DWORD dst_unused:UNUSED_PAD src0_sel:WORD_1 src1_sel:DWORD
	v_add3_u32 v51, v51, v52, s0
	v_add3_u32 v50, v50, v53, s0
	v_lshrrev_b32_e32 v52, 16, v50
	v_lshrrev_b32_e32 v53, 16, v51
	ds_write_b16_d16_hi v43, v60 offset:4080
	ds_write_b16 v43, v52 offset:21216
	ds_write_b16 v43, v53 offset:21488
	v_perm_b32 v53, v51, v50, s19
	v_perm_b32 v52, v54, v55, s19
	v_perm_b32 v51, v56, v57, s19
	v_perm_b32 v50, v58, v59, s19
	ds_write_b128 v94, v[50:53] offset:34832
	s_waitcnt lgkmcnt(0)
	s_barrier
	s_and_saveexec_b64 s[6:7], s[42:43]
	s_cbranch_execz .LBB0_468
	ds_read_b128 v[50:53], v95
	ds_read_b128 v[54:57], v95 offset:64
	ds_read_b128 v[58:61], v95 offset:128
	ds_read_b128 v[62:65], v95 offset:192
	ds_read_b128 v[66:69], v99 offset:17408
	ds_read_b128 v[102:105], v99 offset:17472
	ds_read_b128 v[106:109], v99 offset:17536
	ds_read_b128 v[110:113], v99 offset:17600
	ds_read_b128 v[114:117], v99 offset:21760
	ds_read_b128 v[118:121], v99 offset:21824
	ds_read_b128 v[126:129], v99 offset:21888
	ds_read_b128 v[130:133], v99 offset:21952
	ds_read_b128 v[134:137], v96 offset:34816
	ds_read_b128 v[138:141], v96 offset:34880
	ds_read_b128 v[142:145], v96 offset:37120
	ds_read_b128 v[146:149], v96 offset:37184
	v_add_u32_e32 v101, v75, v83
	ds_read_b128 v[150:153], v101 offset:53248
	ds_read_b128 v[154:157], v101 offset:53312
	ds_read_b128 v[158:161], v101 offset:55552
	ds_read_b128 v[164:167], v101 offset:55616
	s_waitcnt lgkmcnt(14)
	v_mfma_f32_16x16x32_bf16 v[66:69], v[66:69], v[50:53], 0
	v_mfma_f32_16x16x32_bf16 v[66:69], v[102:105], v[54:57], v[66:69]
	s_waitcnt lgkmcnt(11)
	v_mfma_f32_16x16x32_bf16 v[102:105], v[114:117], v[50:53], 0
	s_waitcnt lgkmcnt(10)
	v_mfma_f32_16x16x32_bf16 v[102:105], v[118:121], v[54:57], v[102:105]
	s_waitcnt lgkmcnt(3)
	v_mfma_f32_16x16x32_bf16 v[22:25], v[134:137], v[150:153], v[22:25]
	s_waitcnt lgkmcnt(1)
	v_mfma_f32_16x16x32_bf16 v[26:29], v[134:137], v[158:161], v[26:29]
	v_mfma_f32_16x16x32_bf16 v[30:33], v[142:145], v[150:153], v[30:33]
	v_mfma_f32_16x16x32_bf16 v[34:37], v[142:145], v[158:161], v[34:37]
	v_mfma_f32_16x16x32_bf16 v[66:69], v[106:109], v[58:61], v[66:69]
	v_mfma_f32_16x16x32_bf16 v[102:105], v[126:129], v[58:61], v[102:105]
	v_mfma_f32_16x16x32_bf16 v[22:25], v[138:141], v[154:157], v[22:25]
	s_waitcnt lgkmcnt(0)
	v_mfma_f32_16x16x32_bf16 v[26:29], v[138:141], v[164:167], v[26:29]
	v_mfma_f32_16x16x32_bf16 v[30:33], v[146:149], v[154:157], v[30:33]
	v_mfma_f32_16x16x32_bf16 v[34:37], v[146:149], v[164:167], v[34:37]
	v_mfma_f32_16x16x32_bf16 v[66:69], v[110:113], v[62:65], v[66:69]
	v_mfma_f32_16x16x32_bf16 v[102:105], v[130:133], v[62:65], v[102:105]
	ds_read_b128 v[106:109], v99 offset:26112
	ds_read_b128 v[110:113], v99 offset:26176
	ds_read_b128 v[114:117], v99 offset:26240
	ds_read_b128 v[118:121], v99 offset:26304
	ds_read_b128 v[126:129], v97 offset:26112
	ds_read_b128 v[130:133], v97 offset:26176
	ds_read_b128 v[134:137], v97 offset:26240
	ds_read_b128 v[138:141], v97 offset:26304
	v_add_u32_e32 v101, 0xd000, v98
	ds_read2_b64 v[142:145], v101 offset1:4
	ds_read2_b64 v[146:149], v101 offset0:8 offset1:12
	ds_read_b128 v[150:153], v99 offset:57856
	ds_read_b128 v[154:157], v99 offset:57920
	ds_read_b128 v[158:161], v99 offset:57984
	ds_read_b128 v[164:167], v99 offset:58048
	v_add_u32_e32 v101, 0xd800, v98
	ds_read2_b64 v[168:171], v101 offset0:32 offset1:36
	ds_read2_b64 v[172:175], v101 offset0:40 offset1:44
	ds_read_b128 v[176:179], v99 offset:62208
	ds_read_b128 v[180:183], v99 offset:62272
	ds_read_b128 v[184:187], v99 offset:62336
	ds_read_b128 v[200:203], v99 offset:62400
	s_waitcnt lgkmcnt(14)
	v_mfma_f32_16x16x32_bf16 v[106:109], v[106:109], v[50:53], 0
	v_cndmask_b32_e64 v101, v66, 0, s[50:51]
	v_cndmask_b32_e64 v122, 0, v67, s[48:49]
	v_cndmask_b32_e64 v123, v68, 0, s[54:55]
	v_cndmask_b32_e64 v124, v69, 0, s[52:53]
	v_mfma_f32_16x16x32_bf16 v[66:69], v[110:113], v[54:57], v[106:109]
	v_cndmask_b32_e64 v223, v102, 0, s[58:59]
	v_mfma_f32_16x16x32_bf16 v[66:69], v[114:117], v[58:61], v[66:69]
	v_cndmask_b32_e64 v106, v103, 0, s[56:57]
	v_cndmask_b32_e64 v107, v104, 0, s[62:63]
	v_cndmask_b32_e64 v108, v105, 0, s[60:61]
	v_mfma_f32_16x16x32_bf16 v[66:69], v[118:121], v[62:65], v[66:69]
	v_mov_b32_e32 v111, v106
	v_mov_b32_e32 v110, v107
	v_mfma_f32_16x16x32_bf16 v[102:105], v[126:129], v[50:53], 0
	v_mov_b32_e32 v116, v108
	s_nop 2
	v_cndmask_b32_e64 v117, v66, 0, s[66:67]
	v_cndmask_b32_e64 v118, v67, 0, s[64:65]
	s_waitcnt lgkmcnt(9)
	v_mfma_f32_16x16x32_bf16 v[106:109], v[150:153], v[50:53], 0
	v_cndmask_b32_e64 v119, v68, 0, s[70:71]
	v_cndmask_b32_e64 v120, v69, 0, s[68:69]
	s_waitcnt lgkmcnt(3)
	v_mfma_f32_16x16x32_bf16 v[50:53], v[176:179], v[50:53], 0
	v_mov_b32_e32 v115, v122
	v_mov_b32_e32 v114, v123
	v_mfma_f32_16x16x32_bf16 v[102:105], v[130:133], v[54:57], v[102:105]
	v_mov_b32_e32 v113, v124
	v_mfma_f32_16x16x32_bf16 v[66:69], v[154:157], v[54:57], v[106:109]
	s_waitcnt lgkmcnt(2)
	v_mfma_f32_16x16x32_bf16 v[50:53], v[180:183], v[54:57], v[50:53]
	v_cvt_pk_bf16_f32 v57, v110, v116
	v_cvt_pk_bf16_f32 v56, v223, v111
	v_cvt_pk_bf16_f32 v55, v114, v113
	v_mfma_f32_16x16x32_bf16 v[102:105], v[134:137], v[58:61], v[102:105]
	v_cvt_pk_bf16_f32 v54, v101, v115
	v_mfma_f32_16x16x32_bf16 v[66:69], v[158:161], v[58:61], v[66:69]
	s_waitcnt lgkmcnt(1)
	v_mfma_f32_16x16x32_bf16 v[50:53], v[184:187], v[58:61], v[50:53]
	v_mfma_f32_16x16x32_bf16 v[102:105], v[138:141], v[62:65], v[102:105]
	v_mfma_f32_16x16x32_bf16 v[66:69], v[164:167], v[62:65], v[66:69]
	s_waitcnt lgkmcnt(0)
	v_mfma_f32_16x16x32_bf16 v[50:53], v[200:203], v[62:65], v[50:53]
	s_nop 4
	v_cndmask_b32_e64 v102, v102, 0, s[74:75]
	v_cndmask_b32_e64 v103, v103, 0, s[72:73]
	v_cndmask_b32_e64 v104, v104, 0, s[78:79]
	v_cndmask_b32_e64 v105, v105, 0, s[76:77]
	v_mfma_f32_16x16x32_bf16 v[58:61], v[142:145], v[54:57], v[66:69]
	v_mfma_f32_16x16x32_bf16 v[50:53], v[168:171], v[54:57], v[50:53]
	v_add_u32_e32 v54, s31, v74
	v_cvt_pk_bf16_f32 v65, v104, v105
	v_cvt_pk_bf16_f32 v64, v102, v103
	v_cvt_pk_bf16_f32 v63, v119, v120
	v_cvt_pk_bf16_f32 v62, v117, v118
	v_cmp_lt_i32_e64 s[4:5], s33, v54
	s_nop 0
	v_mfma_f32_16x16x32_bf16 v[58:61], v[146:149], v[62:65], v[58:61]
	v_cndmask_b32_e64 v55, v205, v206, s[4:5]
	v_add_u32_e32 v55, v55, v0
	v_cndmask_b32_e32 v54, v55, v54, vcc
	v_mfma_f32_16x16x32_bf16 v[50:53], v[172:175], v[62:65], v[50:53]
	v_ashrrev_i32_e32 v55, 31, v54
	v_lshl_add_u64 v[54:55], s[2:3], 0, v[54:55]
	s_nop 1
	v_lshlrev_b64 v[54:55], 11, v[54:55]
	v_lshl_add_u64 v[54:55], v[40:41], 0, v[54:55]
	v_cvt_pk_bf16_f32 v57, v60, v61
	v_cvt_pk_bf16_f32 v56, v58, v59
	global_store_dwordx2 v[54:55], v[56:57], off
	v_mov_b32_e32 v58, v51
	v_mov_b32_e32 v51, v52
	v_cvt_pk_bf16_f32 v51, v51, v53
	v_cvt_pk_bf16_f32 v50, v50, v58
	global_store_dwordx2 v[54:55], v[50:51], off offset:32
